# attention: two-group ping-pong (waves 0-3 / 4-7 offset by one phase: softmax VALU phase vs QK+PV MFMA phase), MFMA phase at s_setprio 2, on top of v40
# speedup vs baseline: 1.0051x; 1.0051x over previous
.LBB0_1170:
	v_and_b32_e32 v3, 63, v0
	v_lshrrev_b32_e32 v46, 5, v3
	v_lshlrev_b32_e32 v3, 2, v0
	v_bfe_u32 v4, v0, 2, 2
	v_and_b32_e32 v9, 31, v0
	v_and_or_b32 v3, v3, 12, v4
	v_or_b32_e32 v4, s19, v46
	v_lshl_add_u32 v5, v9, 8, 0
	v_bitop3_b32 v6, v46, v3, s19 bitop3:0x36
	v_lshl_add_u32 v154, v6, 4, v5
	v_bitop3_b32 v6, v4, v3, 2 bitop3:0x36
	v_lshl_add_u32 v155, v6, 4, v5
	v_bitop3_b32 v6, v4, v3, 4 bitop3:0x36
	v_bitop3_b32 v3, v4, v3, 6 bitop3:0x36
	v_lshlrev_b32_e32 v1, 1, v1
	v_lshl_add_u32 v157, v3, 4, v5
	v_and_b32_e32 v1, 2, v1
	v_bfe_u32 v3, v0, 1, 1
	v_lshl_add_u32 v156, v6, 4, v5
	v_bitop3_b32 v5, v1, v46, v3 bitop3:0x36
	v_lshrrev_b32_e32 v2, 2, v2
	v_lshlrev_b32_e32 v47, 4, v5
	v_or_b32_e32 v5, 2, v46
	v_lshlrev_b32_e32 v4, 8, v2
	v_bitop3_b32 v1, v1, v5, v3 bitop3:0x36
	v_lshlrev_b32_e32 v0, 3, v0
	v_lshl_or_b32 v4, v46, 10, v4
	v_lshlrev_b32_e32 v1, 4, v1
	s_movk_i32 s61, 0x800
	v_readlane_b32 s40, v253, 4
	v_and_or_b32 v0, v0, 8, 0
	v_lshlrev_b32_e32 v2, 6, v2
	v_or3_b32 v159, v4, v1, s61
	s_movk_i32 s61, 0x80
	s_add_i32 s40, s40, s3
	v_xad_u32 v162, v2, s61, v0
	s_movk_i32 s61, 0xc0
	s_sub_i32 s38, s15, s3
	s_min_u32 s15, s40, s15
	v_xad_u32 v163, v2, s61, v0
	s_mov_b32 s61, s25
	s_add_i32 s35, s35, s15
	v_add_u32_e32 v158, v0, v2
	v_xad_u32 v160, v2, 64, v0
	s_waitcnt vmcnt(0) lgkmcnt(0)
	s_barrier
	s_lshr_b32 s15, s35, 6
	v_add_u32_e32 v10, s61, v154
	v_add_u32_e32 v22, s61, v155
	v_add_u32_e32 v34, s61, v156
	s_or_b32 s35, s3, s13
	v_add_u32_e32 v68, v4, v158
	v_add_u32_e32 v69, v160, v4
	v_add_u32_e32 v70, v162, v4
	v_add_u32_e32 v71, v163, v4
	ds_read_b128 v[0:3], v154
	ds_read_b128 v[4:7], v154 offset:8192
	ds_read_b128 v[10:13], v10
	ds_read_b128 v[14:17], v155
	ds_read_b128 v[18:21], v155 offset:8192
	ds_read_b128 v[22:25], v22
	ds_read_b128 v[26:29], v156
	ds_read_b128 v[30:33], v156 offset:8192
	ds_read_b128 v[34:37], v34
	ds_read_b128 v[38:41], v157
	ds_read_b128 v[42:45], v157 offset:8192
	v_add_u32_e32 v48, s61, v157
	s_add_i32 vcc_lo, s12, s35
	s_min_i32 s38, s38, 0x80
	ds_read_b128 v[64:67], v48
	s_cmp_lt_i32 s13, s38
	s_cselect_b64 s[40:41], -1, 0
	s_and_b64 s[62:63], s[40:41], exec
	s_mov_b32 s60, 0
	s_cselect_b32 s15, s15, 0
	s_lshr_b32 s17, s17, 6
	s_waitcnt lgkmcnt(9)
	v_mfma_f32_32x32x16_bf16 v[96:111], v[0:3], v[10:13], 0
	s_mov_b32 s61, s60
	s_mov_b32 s62, s60
	s_mov_b32 s63, s60
	s_mov_b32 s64, s60
	s_mov_b32 s65, s60
	s_mov_b32 s66, s60
	s_mov_b32 s67, s60
	v_mfma_f32_32x32x16_bf16 v[80:95], v[4:7], v[10:13], 0
	s_mov_b32 s68, s60
	s_mov_b32 s69, s60
	s_mov_b32 s70, s60
	s_mov_b32 s71, s60
	s_mov_b32 s72, s60
	s_mov_b32 s73, s60
	s_mov_b32 s74, s60
	s_waitcnt lgkmcnt(6)
	v_mfma_f32_32x32x16_bf16 v[96:111], v[14:17], v[22:25], v[96:111]
	s_mov_b32 s75, s60
	v_mov_b64_e32 v[48:49], s[60:61]
	v_mov_b64_e32 v[50:51], s[62:63]
	v_mov_b64_e32 v[52:53], s[64:65]
	v_mov_b64_e32 v[54:55], s[66:67]
	v_mov_b64_e32 v[56:57], s[68:69]
	v_mov_b64_e32 v[58:59], s[70:71]
	v_mfma_f32_32x32x16_bf16 v[80:95], v[18:21], v[22:25], v[80:95]
	v_mov_b64_e32 v[60:61], s[72:73]
	v_mov_b64_e32 v[62:63], s[74:75]
	s_add_i32 s61, s15, -1
	s_add_i32 s72, vcc_lo, 0xffffff66
	s_add_u32 s62, s44, 0x60000
	s_addc_u32 s63, s45, 0
	s_add_i32 s3, s13, s3
	s_waitcnt lgkmcnt(3)
	v_mfma_f32_32x32x16_bf16 v[96:111], v[26:29], v[34:37], v[96:111]
	s_add_i32 s3, s3, s12
	s_waitcnt vmcnt(0) lgkmcnt(0)
	s_barrier
	v_lshlrev_b32_e32 v0, 4, v46
	v_add_lshl_u32 v1, s3, v9, 2
	v_sub_u32_e32 v0, v0, v1
	v_mfma_f32_32x32x16_bf16 v[80:95], v[30:33], v[34:37], v[80:95]
	s_add_u32 s64, s42, 0x40000
	v_add_u32_e32 v166, v47, v68
	v_add_u32_e32 v167, v47, v69
	v_add_u32_e32 v168, v47, v70
	v_add_u32_e32 v169, v47, v71
	v_mov_b64_e32 v[16:17], v[48:49]
	v_add_u32_e32 v164, 0, v0
	s_waitcnt lgkmcnt(0)
	v_mfma_f32_32x32x16_bf16 v[96:111], v[38:41], v[64:67], v[96:111]
	s_addc_u32 s65, s43, 0
	v_mov_b32_e32 v165, 0
	v_mov_b64_e32 v[18:19], v[50:51]
	v_mov_b64_e32 v[20:21], v[52:53]
	v_mov_b64_e32 v[22:23], v[54:55]
	v_mov_b64_e32 v[24:25], v[56:57]
	v_mov_b64_e32 v[26:27], v[58:59]
	v_mfma_f32_32x32x16_bf16 v[80:95], v[42:45], v[64:67], v[80:95]
	v_mov_b64_e32 v[78:79], v[62:63]
	v_mov_b64_e32 v[32:33], v[48:49]
	v_mov_b64_e32 v[76:77], v[60:61]
	v_mov_b64_e32 v[74:75], v[58:59]
	v_mov_b64_e32 v[72:73], v[56:57]
	v_mov_b64_e32 v[70:71], v[54:55]
	v_mov_b64_e32 v[68:69], v[52:53]
	v_mov_b64_e32 v[66:67], v[50:51]
	v_mov_b64_e32 v[64:65], v[48:49]
	v_mov_b64_e32 v[34:35], v[50:51]
	v_mov_b64_e32 v[36:37], v[52:53]
	v_mov_b64_e32 v[38:39], v[54:55]
	v_mov_b64_e32 v[40:41], v[56:57]
	v_mov_b64_e32 v[42:43], v[58:59]
	v_mov_b64_e32 v[44:45], v[60:61]
	v_mov_b64_e32 v[46:47], v[62:63]
	v_mov_b64_e32 v[28:29], v[60:61]
	v_mov_b64_e32 v[30:31], v[62:63]
	v_mov_b32_e32 v161, 0
	v_add_u32_e32 v158, v159, v158
	v_add_u32_e32 v160, v159, v160
	v_add_u32_e32 v162, v159, v162
	v_add_u32_e32 v163, v159, v163
	v_add_u32_e32 v250, s25, v154
	ds_read_b128 v[238:241], v250
	v_add_u32_e32 v250, s25, v155
	ds_read_b128 v[242:245], v250
	v_add_u32_e32 v250, s25, v156
	ds_read_b128 v[246:249], v250
	v_add_u32_e32 v250, s25, v157
	ds_read_b128 v[234:237], v250
	s_waitcnt lgkmcnt(0)
	s_cmp_eq_u32 s19, 0
	s_cbranch_scc1 .Lpp_entry
	s_barrier
.Lpp_entry:
.LBB0_1171:
	s_add_i32 s12, s74, 2
	s_cmp_lt_u32 s12, s17
	s_cselect_b64 s[68:69], -1, 0
	s_cmp_ge_u32 s12, s17
	s_cselect_b64 s[66:67], -1, 0
	s_add_i32 s75, s74, 1
	s_cmp_lt_u32 s75, s17
	s_cselect_b64 s[70:71], -1, 0
	s_cmp_eq_u32 s19, 0
	s_cbranch_scc1 .LBB0_1173
	s_and_b64 vcc, exec, s[66:67]
	s_cbranch_vccnz .Lpp_b0_v
	s_add_u32 s0, s62, 0xfffe0000
	s_addc_u32 s1, s63, -1
	s_mov_b32 m0, s21
	s_nop 0
	global_load_lds_dwordx4 v150, s[0:1]
	s_mov_b32 m0, s22
	s_nop 0
	global_load_lds_dwordx4 v144, s[0:1]
.Lpp_b0_v:
	s_andn2_b64 vcc, exec, s[70:71]
	s_cbranch_vccnz .Lpp_b0_done
	s_add_u32 s0, s64, 0xfffe0000
	s_addc_u32 s1, s65, -1
	s_mov_b32 m0, s26
	s_nop 0
	global_load_lds_dwordx4 v150, s[0:1]
	s_add_i32 m0, s26, 0x400
	s_nop 0
	global_load_lds_dwordx4 v144, s[0:1]
.Lpp_b0_done:
.LBB0_1173:
	s_cmp_le_i32 s60, s72
	s_cbranch_scc0 .LBB0_1178

.LBB0_1176:
	s_cmp_lt_u32 s74, s15
	s_cselect_b64 vcc, -1, 0
	v_mov_b32_e32 v14, v8
	v_mov_b32_e32 v15, v8
	v_cndmask_b32_e32 v7, v8, v103, vcc
	v_cndmask_b32_e32 v6, v8, v102, vcc
	v_cndmask_b32_e32 v5, v8, v101, vcc
	v_cndmask_b32_e32 v4, v8, v100, vcc
	v_cndmask_b32_e32 v3, v8, v99, vcc
	v_cndmask_b32_e32 v2, v8, v98, vcc
	v_cndmask_b32_e32 v1, v8, v97, vcc
	v_cndmask_b32_e32 v0, v8, v96, vcc
	v_mov_b32_e32 v9, v8
	v_mov_b32_e32 v10, v8
	v_mov_b32_e32 v11, v8
	v_mov_b32_e32 v12, v8
	v_mov_b32_e32 v13, v8
	v_mov_b64_e32 v[110:111], v[14:15]
	v_mov_b32_e32 v80, v8
	v_mov_b32_e32 v81, v8
	v_mov_b32_e32 v82, v8
	v_mov_b32_e32 v83, v8
	v_mov_b32_e32 v84, v8
	v_mov_b32_e32 v85, v8
	v_mov_b32_e32 v86, v8
	v_mov_b32_e32 v87, v8
	v_mov_b32_e32 v88, v8
	v_mov_b32_e32 v89, v8
	v_mov_b32_e32 v90, v8
	v_mov_b32_e32 v91, v8
	v_mov_b32_e32 v92, v8
	v_mov_b32_e32 v93, v8
	v_mov_b32_e32 v94, v8
	v_mov_b32_e32 v95, v8
	v_mov_b64_e32 v[108:109], v[12:13]
	v_mov_b64_e32 v[106:107], v[10:11]
	v_mov_b64_e32 v[104:105], v[8:9]
	v_mov_b64_e32 v[102:103], v[6:7]
	v_mov_b64_e32 v[100:101], v[4:5]
	v_mov_b64_e32 v[98:99], v[2:3]
	v_mov_b64_e32 v[96:97], v[0:1]
	v_cmp_neq_f32_e32 vcc, 0, v165
	s_cbranch_vccnz .LBB0_1180
	s_branch .LBB0_1181
.LBB0_1178:
	v_add_u32_e32 v9, s73, v164
	v_add_u32_e32 v0, 0x10300, v9
	v_add_u32_e32 v2, 0x10308, v9
	v_add_u32_e32 v4, 0x10320, v9
	v_add_u32_e32 v6, 0x10328, v9
	v_add_u32_e32 v10, 0x10340, v9
	v_add_u32_e32 v12, 0x10348, v9
	v_add_u32_e32 v14, 0x10360, v9
	ds_read2_b32 v[0:1], v0 offset1:1
	ds_read2_b32 v[2:3], v2 offset1:1
	ds_read2_b32 v[4:5], v4 offset1:1
	ds_read2_b32 v[6:7], v6 offset1:1
	v_add_u32_e32 v151, 0x10368, v9
	ds_read2_b32 v[10:11], v10 offset1:1
	ds_read2_b32 v[12:13], v12 offset1:1
	ds_read2_b32 v[14:15], v14 offset1:1
	ds_read2_b32 v[170:171], v151 offset1:1
	v_add_u32_e32 v182, 0x10388, v9
	v_add_u32_e32 v184, 0x103a0, v9
	v_add_u32_e32 v186, 0x103a8, v9
	v_add_u32_e32 v172, 0x103c0, v9
	v_add_u32_e32 v174, 0x103c8, v9
	v_add_u32_e32 v176, 0x103e0, v9
	v_add_u32_e32 v151, 0x10380, v9
	v_add_u32_e32 v9, 0x103e8, v9
	ds_read2_b32 v[172:173], v172 offset1:1
	ds_read2_b32 v[174:175], v174 offset1:1
	ds_read2_b32 v[176:177], v176 offset1:1
	ds_read2_b32 v[178:179], v9 offset1:1
	ds_read2_b32 v[180:181], v151 offset1:1
	ds_read2_b32 v[182:183], v182 offset1:1
	ds_read2_b32 v[184:185], v184 offset1:1
	ds_read2_b32 v[186:187], v186 offset1:1
	s_waitcnt lgkmcnt(4)
	v_pk_add_f32 v[94:95], v[94:95], v[178:179]
	v_pk_add_f32 v[92:93], v[92:93], v[176:177]
	v_pk_add_f32 v[90:91], v[90:91], v[174:175]
	v_pk_add_f32 v[88:89], v[88:89], v[172:173]
	s_waitcnt lgkmcnt(0)
	v_pk_add_f32 v[86:87], v[86:87], v[186:187]
	v_pk_add_f32 v[84:85], v[84:85], v[184:185]
	v_pk_add_f32 v[82:83], v[82:83], v[182:183]
	v_pk_add_f32 v[80:81], v[80:81], v[180:181]
	v_pk_add_f32 v[110:111], v[110:111], v[170:171]
	v_pk_add_f32 v[108:109], v[108:109], v[14:15]
	v_pk_add_f32 v[106:107], v[106:107], v[12:13]
	v_pk_add_f32 v[104:105], v[104:105], v[10:11]
	v_pk_add_f32 v[102:103], v[102:103], v[6:7]
	v_pk_add_f32 v[100:101], v[100:101], v[4:5]
	v_pk_add_f32 v[98:99], v[98:99], v[2:3]
	v_pk_add_f32 v[96:97], v[96:97], v[0:1]
	s_cmp_lt_i32 s74, s61
	s_cbranch_scc0 .LBB0_1176

.LBB0_1183:
	s_andn2_b64 s[42:43], exec, s[70:71]
	v_exp_f32_e32 v96, v96
	v_exp_f32_e32 v80, v80
	v_exp_f32_e32 v97, v97
	v_exp_f32_e32 v81, v81
	v_add_f32_e32 v9, 0, v96
	v_exp_f32_e32 v98, v98
	v_add_f32_e32 v9, v80, v9
	v_exp_f32_e32 v82, v82
	v_add_f32_e32 v9, v97, v9
	v_exp_f32_e32 v99, v99
	v_add_f32_e32 v9, v81, v9
	v_exp_f32_e32 v83, v83
	v_add_f32_e32 v9, v98, v9
	v_exp_f32_e32 v100, v100
	v_add_f32_e32 v9, v82, v9
	v_exp_f32_e32 v84, v84
	v_add_f32_e32 v9, v99, v9
	v_exp_f32_e32 v101, v101
	v_add_f32_e32 v9, v83, v9
	v_exp_f32_e32 v85, v85
	v_add_f32_e32 v9, v100, v9
	v_exp_f32_e32 v102, v102
	v_add_f32_e32 v9, v84, v9
	v_exp_f32_e32 v86, v86
	v_add_f32_e32 v9, v101, v9
	v_exp_f32_e32 v103, v103
	v_add_f32_e32 v9, v85, v9
	v_exp_f32_e32 v87, v87
	v_add_f32_e32 v9, v102, v9
	v_exp_f32_e32 v104, v104
	v_add_f32_e32 v9, v86, v9
	v_exp_f32_e32 v88, v88
	v_add_f32_e32 v9, v103, v9
	v_exp_f32_e32 v105, v105
	v_add_f32_e32 v9, v87, v9
	v_exp_f32_e32 v89, v89
	v_add_f32_e32 v9, v104, v9
	v_exp_f32_e32 v106, v106
	v_add_f32_e32 v9, v88, v9
	v_exp_f32_e32 v90, v90
	v_add_f32_e32 v9, v105, v9
	v_exp_f32_e32 v107, v107
	v_add_f32_e32 v9, v89, v9
	v_exp_f32_e32 v91, v91
	v_add_f32_e32 v9, v106, v9
	v_exp_f32_e32 v108, v108
	v_add_f32_e32 v9, v90, v9
	v_exp_f32_e32 v92, v92
	v_add_f32_e32 v9, v107, v9
	v_exp_f32_e32 v109, v109
	v_add_f32_e32 v9, v91, v9
	v_exp_f32_e32 v93, v93
	v_add_f32_e32 v9, v108, v9
	v_exp_f32_e32 v110, v110
	v_add_f32_e32 v9, v92, v9
	v_exp_f32_e32 v94, v94
	v_add_f32_e32 v9, v109, v9
	v_exp_f32_e32 v111, v111
	v_add_f32_e32 v9, v93, v9
	v_exp_f32_e32 v95, v95
	v_add_f32_e32 v9, v110, v9
	v_add_f32_e32 v9, v94, v9
	v_add_f32_e32 v9, v111, v9
	v_add_f32_e32 v9, v95, v9
	v_add_f32_e32 v161, v161, v9
	s_cmp_lg_u32 s19, 0
	s_cbranch_scc1 .Lpp_x0
	s_waitcnt vmcnt(0)
.Lpp_x0:
	s_barrier
	s_cbranch_scc1 .Lpp_a0_done
	s_and_b64 vcc, exec, s[66:67]
	s_cbranch_vccnz .Lpp_a0_v
	s_add_u32 s0, s62, 0xfffe0000
	s_addc_u32 s1, s63, -1
	s_mov_b32 m0, s21
	s_nop 0
	global_load_lds_dwordx4 v150, s[0:1]
	s_mov_b32 m0, s22
	s_nop 0
	global_load_lds_dwordx4 v144, s[0:1]

.Lpp_a0_done:
	s_setprio 2
	s_andn2_b64 vcc, exec, s[70:71]
	s_cbranch_vccnz .LBB0_1185
	ds_read_b128 v[0:3], v154 offset:16384
	ds_read_b128 v[4:7], v154 offset:24576
	ds_read_b128 v[170:173], v155 offset:16384
	ds_read_b128 v[174:177], v155 offset:24576
	ds_read_b128 v[182:185], v156 offset:16384
	ds_read_b128 v[186:189], v156 offset:24576
	ds_read_b128 v[194:197], v157 offset:16384
	ds_read_b128 v[226:229], v157 offset:24576
	s_waitcnt lgkmcnt(6)
	v_mfma_f32_32x32x16_bf16 v[128:143], v[0:3], v[238:241], 0
	v_mfma_f32_32x32x16_bf16 v[112:127], v[4:7], v[238:241], 0
	s_waitcnt lgkmcnt(4)
	v_mfma_f32_32x32x16_bf16 v[128:143], v[170:173], v[242:245], v[128:143]
	v_mfma_f32_32x32x16_bf16 v[112:127], v[174:177], v[242:245], v[112:127]
	s_waitcnt lgkmcnt(2)
	v_mfma_f32_32x32x16_bf16 v[128:143], v[182:185], v[246:249], v[128:143]
	v_mfma_f32_32x32x16_bf16 v[112:127], v[186:189], v[246:249], v[112:127]
	s_waitcnt lgkmcnt(0)
	v_mfma_f32_32x32x16_bf16 v[128:143], v[194:197], v[234:237], v[128:143]
	v_mfma_f32_32x32x16_bf16 v[112:127], v[226:229], v[234:237], v[112:127]
.LBB0_1185:
	ds_read_b64_tr_b16 v[0:1], v166 offset:32768
	ds_read_b64_tr_b16 v[2:3], v158 offset:32768
	ds_read_b64_tr_b16 v[4:5], v167 offset:32768
	ds_read_b64_tr_b16 v[6:7], v160 offset:32768
	ds_read_b64_tr_b16 v[10:11], v168 offset:32768
	ds_read_b64_tr_b16 v[12:13], v162 offset:32768
	ds_read_b64_tr_b16 v[174:175], v169 offset:32768
	ds_read_b64_tr_b16 v[176:177], v163 offset:32768
	ds_read_b64_tr_b16 v[178:179], v166 offset:36864
	ds_read_b64_tr_b16 v[180:181], v158 offset:36864
	ds_read_b64_tr_b16 v[182:183], v167 offset:36864
	ds_read_b64_tr_b16 v[184:185], v160 offset:36864
	ds_read_b64_tr_b16 v[186:187], v168 offset:36864
	ds_read_b64_tr_b16 v[188:189], v162 offset:36864
	ds_read_b64_tr_b16 v[190:191], v169 offset:36864
	ds_read_b64_tr_b16 v[192:193], v163 offset:36864
	v_cvt_pk_bf16_f32 v194, v96, v97
	v_cvt_pk_bf16_f32 v195, v98, v99
	v_cvt_pk_bf16_f32 v196, v100, v101
	v_cvt_pk_bf16_f32 v197, v102, v103
	s_waitcnt lgkmcnt(14)
	s_nop 0
	v_mfma_f32_32x32x16_bf16 v[48:63], v[0:3], v[194:197], v[48:63]
	s_waitcnt lgkmcnt(12)
	v_mfma_f32_32x32x16_bf16 v[64:79], v[4:7], v[194:197], v[64:79]
	s_waitcnt lgkmcnt(10)
	v_mfma_f32_32x32x16_bf16 v[32:47], v[10:13], v[194:197], v[32:47]
	s_waitcnt lgkmcnt(8)
	v_mfma_f32_32x32x16_bf16 v[16:31], v[174:177], v[194:197], v[16:31]
	ds_read_b64_tr_b16 v[0:1], v166 offset:40960
	ds_read_b64_tr_b16 v[2:3], v158 offset:40960
	ds_read_b64_tr_b16 v[4:5], v167 offset:40960
	ds_read_b64_tr_b16 v[6:7], v160 offset:40960
	ds_read_b64_tr_b16 v[10:11], v168 offset:40960
	ds_read_b64_tr_b16 v[12:13], v162 offset:40960
	ds_read_b64_tr_b16 v[174:175], v169 offset:40960
	ds_read_b64_tr_b16 v[176:177], v163 offset:40960
	v_cvt_pk_bf16_f32 v194, v104, v105
	v_cvt_pk_bf16_f32 v195, v106, v107
	v_cvt_pk_bf16_f32 v196, v108, v109
	v_cvt_pk_bf16_f32 v197, v110, v111
	s_waitcnt lgkmcnt(14)
	s_nop 0
	v_mfma_f32_32x32x16_bf16 v[48:63], v[178:181], v[194:197], v[48:63]
	s_waitcnt lgkmcnt(12)
	v_mfma_f32_32x32x16_bf16 v[64:79], v[182:185], v[194:197], v[64:79]
	s_waitcnt lgkmcnt(10)
	v_mfma_f32_32x32x16_bf16 v[32:47], v[186:189], v[194:197], v[32:47]
	s_waitcnt lgkmcnt(8)
	v_mfma_f32_32x32x16_bf16 v[16:31], v[190:193], v[194:197], v[16:31]
	ds_read_b64_tr_b16 v[178:179], v166 offset:45056
	ds_read_b64_tr_b16 v[180:181], v158 offset:45056
	ds_read_b64_tr_b16 v[182:183], v167 offset:45056
	ds_read_b64_tr_b16 v[184:185], v160 offset:45056
	ds_read_b64_tr_b16 v[186:187], v168 offset:45056
	ds_read_b64_tr_b16 v[188:189], v162 offset:45056
	ds_read_b64_tr_b16 v[190:191], v169 offset:45056
	ds_read_b64_tr_b16 v[192:193], v163 offset:45056
	v_cvt_pk_bf16_f32 v194, v80, v81
	v_cvt_pk_bf16_f32 v195, v82, v83
	v_cvt_pk_bf16_f32 v196, v84, v85
	v_cvt_pk_bf16_f32 v197, v86, v87
	s_waitcnt lgkmcnt(14)
	s_nop 0
	v_mfma_f32_32x32x16_bf16 v[48:63], v[0:3], v[194:197], v[48:63]
	s_waitcnt lgkmcnt(12)
	v_mfma_f32_32x32x16_bf16 v[64:79], v[4:7], v[194:197], v[64:79]
	s_waitcnt lgkmcnt(10)
	v_mfma_f32_32x32x16_bf16 v[32:47], v[10:13], v[194:197], v[32:47]
	s_waitcnt lgkmcnt(8)
	v_mfma_f32_32x32x16_bf16 v[16:31], v[174:177], v[194:197], v[16:31]
	v_cvt_pk_bf16_f32 v0, v88, v89
	v_cvt_pk_bf16_f32 v1, v90, v91
	v_cvt_pk_bf16_f32 v2, v92, v93
	v_cvt_pk_bf16_f32 v3, v94, v95
	s_cmp_eq_u32 s19, 0
	s_waitcnt lgkmcnt(0)
	s_cbranch_scc1 .Lpp_y0
	s_waitcnt vmcnt(0)
.Lpp_y0:
	s_barrier
	s_waitcnt lgkmcnt(6)
	v_mfma_f32_32x32x16_bf16 v[48:63], v[178:181], v[0:3], v[48:63]
	s_and_b64 vcc, exec, s[42:43]
	s_waitcnt lgkmcnt(4)
	v_mfma_f32_32x32x16_bf16 v[64:79], v[182:185], v[0:3], v[64:79]
	s_waitcnt lgkmcnt(2)
	v_mfma_f32_32x32x16_bf16 v[32:47], v[186:189], v[0:3], v[32:47]
	s_waitcnt lgkmcnt(0)
	v_mfma_f32_32x32x16_bf16 v[16:31], v[190:193], v[0:3], v[16:31]
	s_setprio 0
	s_cbranch_vccnz .LBB0_1197
	s_andn2_b64 s[42:43], exec, s[68:69]
	s_cmp_eq_u32 s19, 0
	s_cbranch_scc1 .LBB0_1188
	s_add_i32 s3, s74, 3
	s_cmp_ge_u32 s3, s17
	s_cbranch_scc1 .Lpp_b1_v
	s_mov_b32 m0, s27
	s_nop 0
	global_load_lds_dwordx4 v150, s[62:63]
	s_add_i32 m0, s27, 0x400
	s_nop 0
	global_load_lds_dwordx4 v144, s[62:63]
.Lpp_b1_v:
	s_andn2_b64 vcc, exec, s[68:69]
	s_cbranch_vccnz .Lpp_b1_done
	s_mov_b32 m0, s23
	s_nop 0
	global_load_lds_dwordx4 v150, s[64:65]
	s_mov_b32 m0, s24
	s_nop 0
	global_load_lds_dwordx4 v144, s[64:65]
.Lpp_b1_done:
.LBB0_1188:
	s_add_i32 s3, s60, 64
	s_cmp_le_i32 s3, s72
	s_cbranch_scc1 .LBB0_1201

.LBB0_1194:
	v_exp_f32_e32 v128, v128
	v_exp_f32_e32 v112, v112
	v_exp_f32_e32 v129, v129
	v_exp_f32_e32 v113, v113
	v_add_f32_e32 v9, 0, v128
	v_exp_f32_e32 v130, v130
	v_add_f32_e32 v9, v112, v9
	v_exp_f32_e32 v114, v114
	v_add_f32_e32 v9, v129, v9
	v_exp_f32_e32 v131, v131
	v_add_f32_e32 v9, v113, v9
	v_exp_f32_e32 v115, v115
	v_add_f32_e32 v9, v130, v9
	v_exp_f32_e32 v132, v132
	v_add_f32_e32 v9, v114, v9
	v_exp_f32_e32 v116, v116
	v_add_f32_e32 v9, v131, v9
	v_exp_f32_e32 v133, v133
	v_add_f32_e32 v9, v115, v9
	v_exp_f32_e32 v117, v117
	v_add_f32_e32 v9, v132, v9
	v_exp_f32_e32 v134, v134
	v_add_f32_e32 v9, v116, v9
	v_exp_f32_e32 v118, v118
	v_add_f32_e32 v9, v133, v9
	v_exp_f32_e32 v135, v135
	v_add_f32_e32 v9, v117, v9
	v_exp_f32_e32 v119, v119
	v_add_f32_e32 v9, v134, v9
	v_exp_f32_e32 v136, v136
	v_add_f32_e32 v9, v118, v9
	v_exp_f32_e32 v120, v120
	v_add_f32_e32 v9, v135, v9
	v_exp_f32_e32 v137, v137
	v_add_f32_e32 v9, v119, v9
	v_exp_f32_e32 v121, v121
	v_add_f32_e32 v9, v136, v9
	v_exp_f32_e32 v138, v138
	v_add_f32_e32 v9, v120, v9
	v_exp_f32_e32 v122, v122
	v_add_f32_e32 v9, v137, v9
	v_exp_f32_e32 v139, v139
	v_add_f32_e32 v9, v121, v9
	v_exp_f32_e32 v123, v123
	v_add_f32_e32 v9, v138, v9
	v_exp_f32_e32 v140, v140
	v_add_f32_e32 v9, v122, v9
	v_exp_f32_e32 v124, v124
	v_add_f32_e32 v9, v139, v9
	v_exp_f32_e32 v141, v141
	v_add_f32_e32 v9, v123, v9
	v_exp_f32_e32 v125, v125
	v_add_f32_e32 v9, v140, v9
	v_exp_f32_e32 v142, v142
	v_add_f32_e32 v9, v124, v9
	v_exp_f32_e32 v126, v126
	v_add_f32_e32 v9, v141, v9
	v_exp_f32_e32 v143, v143
	v_add_f32_e32 v9, v125, v9
	v_exp_f32_e32 v127, v127
	v_add_f32_e32 v9, v142, v9
	v_add_f32_e32 v9, v126, v9
	v_add_f32_e32 v9, v143, v9
	v_add_f32_e32 v9, v127, v9
	v_add_f32_e32 v161, v161, v9
	s_cmp_lg_u32 s19, 0
	s_cbranch_scc1 .Lpp_x1
	s_waitcnt vmcnt(0)
.Lpp_x1:
	s_barrier
	s_cbranch_scc1 .Lpp_a1_done
	s_add_i32 s3, s74, 3
	s_cmp_ge_u32 s3, s17
	s_cbranch_scc1 .Lpp_a1_v
	s_mov_b32 m0, s27
	s_nop 0
	global_load_lds_dwordx4 v150, s[62:63]
	s_add_i32 m0, s27, 0x400
	s_nop 0
	global_load_lds_dwordx4 v144, s[62:63]

.Lpp_a1_done:
	s_setprio 2
	s_and_b64 vcc, exec, s[42:43]
	s_cbranch_vccnz .LBB0_1196
	ds_read_b128 v[0:3], v154
	ds_read_b128 v[4:7], v154 offset:8192
	ds_read_b128 v[174:177], v155
	ds_read_b128 v[178:181], v155 offset:8192
	ds_read_b128 v[186:189], v156
	ds_read_b128 v[190:193], v156 offset:8192
	ds_read_b128 v[226:229], v157
	ds_read_b128 v[230:233], v157 offset:8192
	s_waitcnt lgkmcnt(6)
	v_mfma_f32_32x32x16_bf16 v[96:111], v[0:3], v[238:241], 0
	v_mfma_f32_32x32x16_bf16 v[80:95], v[4:7], v[238:241], 0
	s_waitcnt lgkmcnt(4)
	v_mfma_f32_32x32x16_bf16 v[96:111], v[174:177], v[242:245], v[96:111]
	v_mfma_f32_32x32x16_bf16 v[80:95], v[178:181], v[242:245], v[80:95]
	s_waitcnt lgkmcnt(2)
	v_mfma_f32_32x32x16_bf16 v[96:111], v[186:189], v[246:249], v[96:111]
	v_mfma_f32_32x32x16_bf16 v[80:95], v[190:193], v[246:249], v[80:95]
	s_waitcnt lgkmcnt(0)
	v_mfma_f32_32x32x16_bf16 v[96:111], v[226:229], v[234:237], v[96:111]
	v_mfma_f32_32x32x16_bf16 v[80:95], v[230:233], v[234:237], v[80:95]
.LBB0_1196:
	ds_read_b64_tr_b16 v[0:1], v166 offset:49152
	ds_read_b64_tr_b16 v[2:3], v158 offset:49152
	ds_read_b64_tr_b16 v[4:5], v167 offset:49152
	ds_read_b64_tr_b16 v[6:7], v160 offset:49152
	ds_read_b64_tr_b16 v[10:11], v168 offset:49152
	ds_read_b64_tr_b16 v[12:13], v162 offset:49152
	ds_read_b64_tr_b16 v[174:175], v169 offset:49152
	ds_read_b64_tr_b16 v[176:177], v163 offset:49152
	ds_read_b64_tr_b16 v[178:179], v166 offset:53248
	ds_read_b64_tr_b16 v[180:181], v158 offset:53248
	ds_read_b64_tr_b16 v[182:183], v167 offset:53248
	ds_read_b64_tr_b16 v[184:185], v160 offset:53248
	ds_read_b64_tr_b16 v[186:187], v168 offset:53248
	ds_read_b64_tr_b16 v[188:189], v162 offset:53248
	ds_read_b64_tr_b16 v[190:191], v169 offset:53248
	ds_read_b64_tr_b16 v[192:193], v163 offset:53248
	v_cvt_pk_bf16_f32 v194, v128, v129
	v_cvt_pk_bf16_f32 v195, v130, v131
	v_cvt_pk_bf16_f32 v196, v132, v133
	v_cvt_pk_bf16_f32 v197, v134, v135
	s_waitcnt lgkmcnt(14)
	s_nop 0
	v_mfma_f32_32x32x16_bf16 v[48:63], v[0:3], v[194:197], v[48:63]
	s_waitcnt lgkmcnt(12)
	v_mfma_f32_32x32x16_bf16 v[64:79], v[4:7], v[194:197], v[64:79]
	s_waitcnt lgkmcnt(10)
	v_mfma_f32_32x32x16_bf16 v[32:47], v[10:13], v[194:197], v[32:47]
	s_waitcnt lgkmcnt(8)
	v_mfma_f32_32x32x16_bf16 v[16:31], v[174:177], v[194:197], v[16:31]
	ds_read_b64_tr_b16 v[0:1], v166 offset:57344
	ds_read_b64_tr_b16 v[2:3], v158 offset:57344
	ds_read_b64_tr_b16 v[4:5], v167 offset:57344
	ds_read_b64_tr_b16 v[6:7], v160 offset:57344
	ds_read_b64_tr_b16 v[10:11], v168 offset:57344
	ds_read_b64_tr_b16 v[12:13], v162 offset:57344
	ds_read_b64_tr_b16 v[174:175], v169 offset:57344
	ds_read_b64_tr_b16 v[176:177], v163 offset:57344
	v_cvt_pk_bf16_f32 v194, v136, v137
	v_cvt_pk_bf16_f32 v195, v138, v139
	v_cvt_pk_bf16_f32 v196, v140, v141
	v_cvt_pk_bf16_f32 v197, v142, v143
	s_waitcnt lgkmcnt(14)
	s_nop 0
	v_mfma_f32_32x32x16_bf16 v[48:63], v[178:181], v[194:197], v[48:63]
	s_waitcnt lgkmcnt(12)
	v_mfma_f32_32x32x16_bf16 v[64:79], v[182:185], v[194:197], v[64:79]
	s_waitcnt lgkmcnt(10)
	v_mfma_f32_32x32x16_bf16 v[32:47], v[186:189], v[194:197], v[32:47]
	s_waitcnt lgkmcnt(8)
	v_mfma_f32_32x32x16_bf16 v[16:31], v[190:193], v[194:197], v[16:31]
	ds_read_b64_tr_b16 v[178:179], v166 offset:61440
	ds_read_b64_tr_b16 v[180:181], v158 offset:61440
	ds_read_b64_tr_b16 v[182:183], v167 offset:61440
	ds_read_b64_tr_b16 v[184:185], v160 offset:61440
	ds_read_b64_tr_b16 v[186:187], v168 offset:61440
	ds_read_b64_tr_b16 v[188:189], v162 offset:61440
	ds_read_b64_tr_b16 v[170:171], v169 offset:61440
	ds_read_b64_tr_b16 v[172:173], v163 offset:61440
	v_cvt_pk_bf16_f32 v190, v112, v113
	v_cvt_pk_bf16_f32 v191, v114, v115
	v_cvt_pk_bf16_f32 v192, v116, v117
	v_cvt_pk_bf16_f32 v193, v118, v119
	s_waitcnt lgkmcnt(14)
	s_nop 0
	v_mfma_f32_32x32x16_bf16 v[48:63], v[0:3], v[190:193], v[48:63]
	s_waitcnt lgkmcnt(12)
	v_mfma_f32_32x32x16_bf16 v[64:79], v[4:7], v[190:193], v[64:79]
	s_waitcnt lgkmcnt(10)
	v_mfma_f32_32x32x16_bf16 v[32:47], v[10:13], v[190:193], v[32:47]
	s_waitcnt lgkmcnt(8)
	v_mfma_f32_32x32x16_bf16 v[16:31], v[174:177], v[190:193], v[16:31]
	v_cvt_pk_bf16_f32 v0, v120, v121
	v_cvt_pk_bf16_f32 v1, v122, v123
	v_cvt_pk_bf16_f32 v2, v124, v125
	v_cvt_pk_bf16_f32 v3, v126, v127
	s_cmp_eq_u32 s19, 0
	s_waitcnt lgkmcnt(0)
	s_cbranch_scc1 .Lpp_y1
	s_waitcnt vmcnt(0)
.Lpp_y1:
	s_barrier
	s_waitcnt lgkmcnt(6)
	v_mfma_f32_32x32x16_bf16 v[48:63], v[178:181], v[0:3], v[48:63]
	s_waitcnt lgkmcnt(4)
	v_mfma_f32_32x32x16_bf16 v[64:79], v[182:185], v[0:3], v[64:79]
	s_waitcnt lgkmcnt(2)
	v_mfma_f32_32x32x16_bf16 v[32:47], v[186:189], v[0:3], v[32:47]
	s_waitcnt lgkmcnt(0)
	v_mfma_f32_32x32x16_bf16 v[16:31], v[170:173], v[0:3], v[16:31]
	s_setprio 0
.LBB0_1197:
	s_add_u32 s62, s62, 0x40000
	s_addc_u32 s63, s63, 0
	s_addk_i32 s73, 0x200
	s_addk_i32 s60, 0x80
	s_add_u32 s64, s64, 0x40000
	s_addc_u32 s65, s65, 0
	s_and_b64 vcc, exec, s[66:67]
	s_cbranch_vccnz .LBB0_1203
	s_mov_b32 s74, s12
	s_branch .LBB0_1171
.LBB0_1201:
	s_cmp_lt_i32 s75, s61
	s_cbranch_scc1 .LBB0_1190

.LBB0_1203:
	s_cmp_lg_u32 s19, 0
	s_cbranch_scc1 .Lpp_exit
	s_barrier
